# neighbourhood attention: 16 exec-masked bias-read diamonds per key tile replaced by 16 back-to-back ds_reads + add/cndmask
# speedup vs baseline: 1.0045x; 1.0045x over previous
; #define MFMA32(a, b, c) __builtin_amdgcn_mfma_f32_32x32x16_bf16((a), (b), (c), 0, 0, 0)
; DI float fexp2(float x) { return __builtin_amdgcn_exp2f(x); }
; DI void frag64_load(Frag64& f, const bf16_t* P, const bf16_t* vt, int b, int u, int kcol, int lane) {
;     ...
;     f.k[i] = *(const u32x4*)(P + (size_t)rowOfU(b, u + (lane >> 3) + 8 * i) * NP + kcol + (lane & 7) * 8);
;     f.v[i] = *(const u32x4*)(vt + (size_t)((lane >> 2) + 16 * i) * UA + u + (lane & 3) * 8);
; template <int MODE>
; DI void attn64_wave(const Params& p, int layer, int b, int hq, int qrow0, int t0, const float* rpb_lds, unsigned char* wlds) {
;     ...
;   auto compute_tile = [&](const Frag64& f, int t) {
; #pragma unroll
;     for (int i = 0; i < 4; ++i) {
;       *(u32x4*)(Kw + ((lane >> 3) + 8 * i) * LDS_STRIDE + (lane & 7) * 16) = f.k[i];
;       *(u32x4*)(Vw + ((lane >> 2) + 16 * i) * W64_VSTR + (lane & 3) * 16) = f.v[i];
;     }
;     bf16x8 kf[4], vf[2][2];
; #pragma unroll
;     for (int ks = 0; ks < 4; ++ks) kf[ks] = __builtin_bit_cast(bf16x8, *(const u32x4*)(Kw + pr * LDS_STRIDE + (16 * ks + 8 * hh) * 2));
; #pragma unroll
;     for (int dh = 0; dh < 2; ++dh)
; #pragma unroll
;       for (int s2 = 0; s2 < 2; ++s2) vf[dh][s2] = __builtin_bit_cast(bf16x8, *(const u32x4*)(Vw + (32 * dh + qi) * W64_VSTR + (16 * s2 + 8 * hh) * 2));
;     f32x16 s;
; #pragma unroll
;     for (int i = 0; i < 16; ++i) s[i] = negM2;
; #pragma unroll
;     for (int ks = 0; ks < 4; ++ks) s = MFMA32(kf[ks], qf[ks], s);
;     float pe[16];
;     if (t < 8) {
; #pragma unroll
;       for (int i = 0; i < 16; ++i) pe[i] = fexp2(s[i]);
;     } else if (MODE == 0) {
;       const int kr = rs + ((t - 8) >> 1), hf = (t - 8) & 1;
;       const float* rrow = rpb + (kr - r + 7) * 31 + 15 - c;
; #pragma unroll
;       for (int i = 0; i < 16; ++i) {
;         const int kc = hf * 32 + 16 * (i >> 3) + 8 * hh + (i & 7);
;         const bool valid = (kc >= ws) && (kc < ws + 16);
;         const int kcc = min(max(kc, ws), ws + 15);
;         pe[i] = fexp2(valid ? s[i] + rrow[kcc] : -1e30f);
.LBB0_341:
	v_add_u32_e32 v126, v192, v134
	s_movk_i32 s30, 0x100
	v_mov_b32_e32 v127, s22
	v_mov_b32_e32 v143, s42
	v_cmp_gt_i32_e32 vcc, s30, v126
	v_lshl_add_u64 v[124:125], v[192:193], 1, v[130:131]
	global_load_dwordx4 v[116:119], v[124:125], off
	v_cndmask_b32_e32 v48, v127, v143, vcc
	v_add_u32_e32 v48, v48, v126
	v_mad_i64_i32 v[48:49], s[30:31], v48, s20, v[128:129]
	s_movk_i32 s30, 0xf8
	s_nop 0
	v_cmp_gt_i32_e32 vcc, s30, v126
	global_load_dwordx4 v[112:115], v[48:49], off
	s_nop 0
	v_cndmask_b32_e32 v48, v127, v143, vcc
	v_add3_u32 v48, v126, v48, 8
	v_mad_i64_i32 v[48:49], s[30:31], v48, s20, v[128:129]
	global_load_dwordx4 v[120:123], v[48:49], off
	s_waitcnt vmcnt(9)
	ds_write_b128 v139, v[84:87] offset:8192
	ds_write_b128 v140, v[80:83] offset:12800
	s_waitcnt vmcnt(8)
	ds_write_b128 v139, v[88:91] offset:9344
	s_waitcnt vmcnt(7)
	ds_write_b128 v140, v[92:95] offset:14080
	s_waitcnt vmcnt(6)
	ds_write_b128 v139, v[96:99] offset:10496
	s_waitcnt vmcnt(5)
	ds_write_b128 v140, v[100:103] offset:15360
	s_waitcnt vmcnt(4)
	ds_write_b128 v139, v[104:107] offset:11648
	s_waitcnt vmcnt(3)
	ds_write_b128 v140, v[108:111] offset:16640
	ds_read_b128 v[80:83], v141 offset:8192
	ds_read_b128 v[84:87], v141 offset:8224
	v_add_co_u32_e32 v48, vcc, s89, v124
	s_movk_i32 s30, 0xf0
	s_nop 0
	v_addc_co_u32_e32 v49, vcc, 0, v125, vcc
	v_cmp_gt_i32_e32 vcc, s30, v126
	global_load_dwordx4 v[92:95], v[48:49], off
	ds_read_b128 v[146:149], v141 offset:8288
	v_cndmask_b32_e32 v48, v127, v143, vcc
	v_add3_u32 v48, v126, v48, 16
	v_mad_i64_i32 v[48:49], s[30:31], v48, s20, v[128:129]
	global_load_dwordx4 v[96:99], v[48:49], off
	s_waitcnt lgkmcnt(2)
	v_mfma_f32_32x32x16_bf16 v[48:63], v[80:83], v[72:75], v[32:47]
	v_add_co_u32_e32 v80, vcc, s48, v124
	s_movk_i32 s30, 0xe8
	s_nop 0
	v_addc_co_u32_e32 v81, vcc, 0, v125, vcc
	v_cmp_gt_i32_e32 vcc, s30, v126
	global_load_dwordx4 v[100:103], v[80:81], off
	s_waitcnt lgkmcnt(1)
	v_mfma_f32_32x32x16_bf16 v[48:63], v[84:87], v[64:67], v[48:63]
	v_cndmask_b32_e32 v80, v127, v143, vcc
	v_add3_u32 v88, v126, v80, 24
	v_mad_i64_i32 v[84:85], s[30:31], v88, s20, v[128:129]
	global_load_dwordx4 v[104:107], v[84:85], off
	v_add_co_u32_e32 v84, vcc, s49, v124
	ds_read_b128 v[80:83], v141 offset:8256
	s_nop 0
	v_addc_co_u32_e32 v85, vcc, 0, v125, vcc
	global_load_dwordx4 v[108:111], v[84:85], off
	s_waitcnt lgkmcnt(0)
	v_mfma_f32_32x32x16_bf16 v[48:63], v[80:83], v[68:71], v[48:63]
	ds_read_b128 v[88:91], v142 offset:12800
	ds_read_b128 v[80:83], v142 offset:12832
	ds_read_b128 v[124:127], v142 offset:15360
	ds_read_b128 v[84:87], v142 offset:15392
	s_and_b64 vcc, exec, s[28:29]
	v_mfma_f32_32x32x16_bf16 v[48:63], v[146:149], v[76:79], v[48:63]
	s_cbranch_vccz .LBB0_375
	s_add_i32 s30, s43, -8
	s_lshr_b32 s30, s30, 1
	v_add_u32_e32 v143, s30, v137
	s_movk_i32 s30, 0x7c
	v_mad_u64_u32 v[146:147], s[30:31], v143, s30, v[132:133]
	v_mov_b32_e32 v143, 0xf149f2ca
	v_lshl_add_u32 v147, v135, 2, v146
	v_mov_b32_e32 v146, 0xf149f2ca
	ds_read_b32 v166, v147 offset:928
	ds_read_b32 v167, v147 offset:932
	ds_read_b32 v168, v147 offset:936
	ds_read_b32 v169, v147 offset:940
	ds_read_b32 v170, v147 offset:944
	ds_read_b32 v171, v147 offset:948
	ds_read_b32 v172, v147 offset:952
	ds_read_b32 v173, v147 offset:956
	ds_read_b32 v174, v147 offset:992
	ds_read_b32 v175, v147 offset:996
	ds_read_b32 v176, v147 offset:1000
	ds_read_b32 v177, v147 offset:1004
	ds_read_b32 v178, v147 offset:1008
	ds_read_b32 v180, v147 offset:1012
	ds_read_b32 v182, v147 offset:1016
	ds_read_b32 v183, v147 offset:1020
	s_waitcnt lgkmcnt(0)
	v_readlane_b32 s44, v255, 12
	v_readlane_b32 s45, v255, 13
	v_add_f32_e32 v166, v48, v166
	s_nop 0
	v_cndmask_b32_e64 v146, v146, v166, s[44:45]
	v_readlane_b32 s44, v255, 14
	v_readlane_b32 s45, v255, 15
	v_add_f32_e32 v167, v49, v167
	s_nop 0
	v_cndmask_b32_e64 v143, v143, v167, s[44:45]
	v_mov_b32_e32 v149, 0xf149f2ca
	v_mov_b32_e32 v148, 0xf149f2ca
	v_readlane_b32 s44, v255, 16
	v_readlane_b32 s45, v255, 17
	v_add_f32_e32 v168, v50, v168
	s_nop 0
	v_cndmask_b32_e64 v148, v148, v168, s[44:45]
	v_readlane_b32 s44, v255, 18
	v_readlane_b32 s45, v255, 19
	v_add_f32_e32 v169, v51, v169
	s_nop 0
	v_cndmask_b32_e64 v149, v149, v169, s[44:45]
	v_mov_b32_e32 v160, 0xf149f2ca
	v_mov_b32_e32 v159, 0xf149f2ca
	v_readlane_b32 s44, v255, 20
	v_readlane_b32 s45, v255, 21
	v_add_f32_e32 v170, v52, v170
	s_nop 0
	v_cndmask_b32_e64 v159, v159, v170, s[44:45]
	v_readlane_b32 s44, v255, 22
	v_readlane_b32 s45, v255, 23
	v_add_f32_e32 v171, v53, v171
	s_nop 0
	v_cndmask_b32_e64 v160, v160, v171, s[44:45]
	v_mov_b32_e32 v162, 0xf149f2ca
	v_mov_b32_e32 v161, 0xf149f2ca
	v_add_f32_e32 v172, v54, v172
	s_nop 0
	v_cndmask_b32_e64 v161, v161, v172, s[50:51]
	v_add_f32_e32 v173, v55, v173
	s_nop 0
	v_cndmask_b32_e64 v162, v162, v173, s[52:53]
	v_mov_b32_e32 v151, 0xf149f2ca
	v_mov_b32_e32 v163, 0xf149f2ca
	v_add_f32_e32 v174, v56, v174
	s_nop 0
	v_cndmask_b32_e64 v163, v163, v174, s[46:47]
	v_add_f32_e32 v175, v57, v175
	s_nop 0
	v_cndmask_b32_e64 v151, v151, v175, s[0:1]
	v_mov_b32_e32 v157, 0xf149f2ca
	v_mov_b32_e32 v150, 0xf149f2ca
	v_add_f32_e32 v176, v58, v176
	s_nop 0
	v_cndmask_b32_e64 v150, v150, v176, s[90:91]
	v_add_f32_e32 v177, v59, v177
	s_nop 0
	v_cndmask_b32_e64 v157, v157, v177, s[92:93]
	v_mov_b32_e32 v158, 0xf149f2ca
	v_mov_b32_e32 v156, 0xf149f2ca
	v_add_f32_e32 v178, v60, v178
	s_nop 0
	v_cndmask_b32_e64 v156, v156, v178, s[94:95]
	v_add_f32_e32 v180, v61, v180
	s_nop 0
	v_cndmask_b32_e64 v158, v158, v180, s[26:27]
	v_mov_b32_e32 v164, 0xf149f2ca
	v_mov_b32_e32 v165, 0xf149f2ca
	v_add_f32_e32 v182, v62, v182
	s_nop 0
	v_cndmask_b32_e64 v165, v165, v182, s[24:25]
	v_add_f32_e32 v183, v63, v183
	s_nop 0
	v_cndmask_b32_e64 v164, v164, v183, s[72:73]
	v_exp_f32_e32 v158, v158
	v_exp_f32_e32 v156, v156
	v_exp_f32_e32 v157, v157
	v_exp_f32_e32 v150, v150
	v_exp_f32_e32 v151, v151
	v_exp_f32_e32 v147, v163
	v_exp_f32_e32 v163, v162
	v_exp_f32_e32 v161, v161
	v_exp_f32_e32 v162, v160
	v_exp_f32_e32 v159, v159
	v_exp_f32_e32 v160, v149
	v_exp_f32_e32 v148, v148
	v_exp_f32_e32 v149, v143
	v_exp_f32_e32 v143, v146
	v_exp_f32_e32 v146, v165
	s_branch .LBB0_377

; #define MFMA32(a, b, c) __builtin_amdgcn_mfma_f32_32x32x16_bf16((a), (b), (c), 0, 0, 0)
; DI float fexp2(float x) { return __builtin_amdgcn_exp2f(x); }
; DI void frag64_load(Frag64& f, const bf16_t* P, const bf16_t* vt, int b, int u, int kcol, int lane) {
;     ...
;     f.k[i] = *(const u32x4*)(P + (size_t)rowOfU(b, u + (lane >> 3) + 8 * i) * NP + kcol + (lane & 7) * 8);
;     f.v[i] = *(const u32x4*)(vt + (size_t)((lane >> 2) + 16 * i) * UA + u + (lane & 3) * 8);
; template <int MODE>
; DI void attn64_wave(const Params& p, int layer, int b, int hq, int qrow0, int t0, const float* rpb_lds, unsigned char* wlds) {
;     ...
;   auto compute_tile = [&](const Frag64& f, int t) {
; #pragma unroll
;     for (int i = 0; i < 4; ++i) {
;       *(u32x4*)(Kw + ((lane >> 3) + 8 * i) * LDS_STRIDE + (lane & 7) * 16) = f.k[i];
;       *(u32x4*)(Vw + ((lane >> 2) + 16 * i) * W64_VSTR + (lane & 3) * 16) = f.v[i];
;     }
;     bf16x8 kf[4], vf[2][2];
; #pragma unroll
;     for (int ks = 0; ks < 4; ++ks) kf[ks] = __builtin_bit_cast(bf16x8, *(const u32x4*)(Kw + pr * LDS_STRIDE + (16 * ks + 8 * hh) * 2));
; #pragma unroll
;     for (int dh = 0; dh < 2; ++dh)
; #pragma unroll
;       for (int s2 = 0; s2 < 2; ++s2) vf[dh][s2] = __builtin_bit_cast(bf16x8, *(const u32x4*)(Vw + (32 * dh + qi) * W64_VSTR + (16 * s2 + 8 * hh) * 2));
;     f32x16 s;
; #pragma unroll
;     for (int i = 0; i < 16; ++i) s[i] = negM2;
; #pragma unroll
;     for (int ks = 0; ks < 4; ++ks) s = MFMA32(kf[ks], qf[ks], s);
;     float pe[16];
;     if (t < 8) {
; #pragma unroll
;       for (int i = 0; i < 16; ++i) pe[i] = fexp2(s[i]);
;     } else if (MODE == 0) {
;       const int kr = rs + ((t - 8) >> 1), hf = (t - 8) & 1;
;       const float* rrow = rpb + (kr - r + 7) * 31 + 15 - c;
; #pragma unroll
;       for (int i = 0; i < 16; ++i) {
;         const int kc = hf * 32 + 16 * (i >> 3) + 8 * hh + (i & 7);
;         const bool valid = (kc >= ws) && (kc < ws + 16);
;         const int kcc = min(max(kc, ws), ws + 15);
;         pe[i] = fexp2(valid ? s[i] + rrow[kcc] : -1e30f);
.LBB0_381:
	v_add_u32_e32 v126, v48, v134
	s_movk_i32 s45, 0x100
	v_mov_b32_e32 v127, s22
	v_mov_b32_e32 v143, s42
	v_cmp_gt_i32_e32 vcc, s45, v126
	s_movk_i32 s45, 0xf8
	v_ashrrev_i32_e32 v49, 31, v48
	v_cndmask_b32_e32 v50, v127, v143, vcc
	v_add_u32_e32 v50, v50, v126
	v_mad_i64_i32 v[50:51], vcc, v50, s20, v[128:129]
	v_cmp_gt_i32_e32 vcc, s45, v126
	v_lshl_add_u64 v[124:125], v[48:49], 1, v[130:131]
	global_load_dwordx4 v[84:87], v[50:51], off
	v_cndmask_b32_e32 v48, v127, v143, vcc
	v_add3_u32 v48, v126, v48, 8
	v_mad_i64_i32 v[48:49], vcc, v48, s20, v[128:129]
	global_load_dwordx4 v[80:83], v[124:125], off
	global_load_dwordx4 v[88:91], v[48:49], off
	s_waitcnt vmcnt(9)
	ds_write_b128 v139, v[112:115] offset:8192
	ds_write_b128 v140, v[116:119] offset:12800
	s_waitcnt vmcnt(8)
	ds_write_b128 v139, v[120:123] offset:9344
	s_waitcnt vmcnt(7)
	ds_write_b128 v140, v[92:95] offset:14080
	s_waitcnt vmcnt(6)
	ds_write_b128 v139, v[96:99] offset:10496
	s_waitcnt vmcnt(5)
	ds_write_b128 v140, v[100:103] offset:15360
	s_waitcnt vmcnt(4)
	ds_write_b128 v139, v[104:107] offset:11648
	s_waitcnt vmcnt(3)
	ds_write_b128 v140, v[108:111] offset:16640
	ds_read_b128 v[100:103], v141 offset:8192
	ds_read_b128 v[104:107], v141 offset:8224
	v_add_co_u32_e32 v48, vcc, s89, v124
	s_movk_i32 s45, 0xf0
	s_nop 0
	v_addc_co_u32_e32 v49, vcc, 0, v125, vcc
	v_cmp_gt_i32_e32 vcc, s45, v126
	global_load_dwordx4 v[92:95], v[48:49], off
	s_movk_i32 s45, 0xe8
	v_cndmask_b32_e32 v48, v127, v143, vcc
	v_add3_u32 v48, v126, v48, 16
	v_mad_i64_i32 v[48:49], vcc, v48, s20, v[128:129]
	global_load_dwordx4 v[96:99], v[48:49], off
	s_waitcnt lgkmcnt(1)
	v_mfma_f32_32x32x16_bf16 v[48:63], v[100:103], v[72:75], v[32:47]
	v_add_co_u32_e32 v100, vcc, s48, v124
	ds_read_b128 v[146:149], v141 offset:8288
	s_nop 0
	v_addc_co_u32_e32 v101, vcc, 0, v125, vcc
	v_cmp_gt_i32_e32 vcc, s45, v126
	global_load_dwordx4 v[100:103], v[100:101], off
	s_waitcnt lgkmcnt(1)
	v_mfma_f32_32x32x16_bf16 v[48:63], v[104:107], v[64:67], v[48:63]
	v_cndmask_b32_e32 v108, v127, v143, vcc
	v_add3_u32 v112, v126, v108, 24
	ds_read_b128 v[108:111], v141 offset:8256
	v_mad_i64_i32 v[104:105], vcc, v112, s20, v[128:129]
	v_add_co_u32_e32 v112, vcc, s49, v124
	global_load_dwordx4 v[104:107], v[104:105], off
	s_nop 0
	v_addc_co_u32_e32 v113, vcc, 0, v125, vcc
	s_waitcnt lgkmcnt(0)
	v_mfma_f32_32x32x16_bf16 v[48:63], v[108:111], v[68:71], v[48:63]
	global_load_dwordx4 v[108:111], v[112:113], off
	ds_read_b128 v[120:123], v142 offset:12800
	ds_read_b128 v[112:115], v142 offset:12832
	ds_read_b128 v[124:127], v142 offset:15360
	ds_read_b128 v[116:119], v142 offset:15392
	s_and_b64 vcc, exec, s[28:29]
	v_mfma_f32_32x32x16_bf16 v[48:63], v[146:149], v[76:79], v[48:63]
	s_cbranch_vccz .LBB0_415
	s_add_i32 s28, s43, -7
	s_lshr_b32 s28, s28, 1
	v_add_u32_e32 v143, s28, v137
	s_movk_i32 s28, 0x7c
	v_mad_u64_u32 v[146:147], s[28:29], v143, s28, v[132:133]
	v_mov_b32_e32 v143, 0xf149f2ca
	v_lshl_add_u32 v147, v135, 2, v146
	v_mov_b32_e32 v146, 0xf149f2ca
	ds_read_b32 v166, v147 offset:1056
	ds_read_b32 v167, v147 offset:1060
	ds_read_b32 v168, v147 offset:1064
	ds_read_b32 v169, v147 offset:1068
	ds_read_b32 v170, v147 offset:1072
	ds_read_b32 v171, v147 offset:1076
	ds_read_b32 v172, v147 offset:1080
	ds_read_b32 v173, v147 offset:1084
	ds_read_b32 v174, v147 offset:1120
	ds_read_b32 v175, v147 offset:1124
	ds_read_b32 v176, v147 offset:1128
	ds_read_b32 v177, v147 offset:1132
	ds_read_b32 v178, v147 offset:1136
	ds_read_b32 v180, v147 offset:1140
	ds_read_b32 v182, v147 offset:1144
	ds_read_b32 v183, v147 offset:1148
	s_waitcnt lgkmcnt(0)
	v_add_f32_e32 v166, v48, v166
	s_nop 0
	v_cndmask_b32_e64 v146, v146, v166, s[74:75]
	v_add_f32_e32 v167, v49, v167
	s_nop 0
	v_cndmask_b32_e64 v143, v143, v167, s[76:77]
	v_mov_b32_e32 v149, 0xf149f2ca
	v_mov_b32_e32 v148, 0xf149f2ca
	v_add_f32_e32 v168, v50, v168
	s_nop 0
	v_cndmask_b32_e64 v148, v148, v168, s[78:79]
	v_add_f32_e32 v169, v51, v169
	s_nop 0
	v_cndmask_b32_e64 v149, v149, v169, s[80:81]
	v_mov_b32_e32 v151, 0xf149f2ca
	v_mov_b32_e32 v150, 0xf149f2ca
	v_add_f32_e32 v170, v52, v170
	s_nop 0
	v_cndmask_b32_e64 v150, v150, v170, s[82:83]
	v_add_f32_e32 v171, v53, v171
	s_nop 0
	v_cndmask_b32_e64 v151, v151, v171, s[84:85]
	v_mov_b32_e32 v162, 0xf149f2ca
	v_mov_b32_e32 v161, 0xf149f2ca
	v_add_f32_e32 v172, v54, v172
	s_nop 0
	v_cndmask_b32_e64 v161, v161, v172, s[86:87]
	v_add_f32_e32 v173, v55, v173
	s_nop 0
	v_cndmask_b32_e64 v162, v162, v173, s[2:3]
	v_mov_b32_e32 v157, 0xf149f2ca
	v_mov_b32_e32 v163, 0xf149f2ca
	v_add_f32_e32 v174, v56, v174
	s_nop 0
	v_cndmask_b32_e64 v163, v163, v174, s[54:55]
	v_add_f32_e32 v175, v57, v175
	s_nop 0
	v_cndmask_b32_e64 v157, v157, v175, s[56:57]
	v_mov_b32_e32 v159, 0xf149f2ca
	v_mov_b32_e32 v156, 0xf149f2ca
	v_add_f32_e32 v176, v58, v176
	s_nop 0
	v_cndmask_b32_e64 v156, v156, v176, s[58:59]
	v_add_f32_e32 v177, v59, v177
	s_nop 0
	v_cndmask_b32_e64 v159, v159, v177, s[60:61]
	v_mov_b32_e32 v160, 0xf149f2ca
	v_mov_b32_e32 v158, 0xf149f2ca
	v_add_f32_e32 v178, v60, v178
	s_nop 0
	v_cndmask_b32_e64 v158, v158, v178, s[62:63]
	v_add_f32_e32 v180, v61, v180
	s_nop 0
	v_cndmask_b32_e64 v160, v160, v180, s[64:65]
	v_mov_b32_e32 v164, 0xf149f2ca
	v_mov_b32_e32 v165, 0xf149f2ca
	v_add_f32_e32 v182, v62, v182
	s_nop 0
	v_cndmask_b32_e64 v165, v165, v182, s[66:67]
	v_add_f32_e32 v183, v63, v183
	s_nop 0
	v_cndmask_b32_e64 v164, v164, v183, s[68:69]
	v_exp_f32_e32 v160, v160
	v_exp_f32_e32 v158, v158
	v_exp_f32_e32 v159, v159
	v_exp_f32_e32 v156, v156
	v_exp_f32_e32 v157, v157
	v_exp_f32_e32 v147, v163
	v_exp_f32_e32 v163, v162
	v_exp_f32_e32 v161, v161
	v_exp_f32_e32 v162, v151
	v_exp_f32_e32 v150, v150
	v_exp_f32_e32 v151, v149
	v_exp_f32_e32 v148, v148
	v_exp_f32_e32 v149, v143
	v_exp_f32_e32 v143, v146
	v_exp_f32_e32 v146, v165
	s_branch .LBB0_338
